# attention softmax as exp2(s)/sum without the max shift (exact softmax math; scores are O(10)); GEMM accumulator zeroing with v_pk_mov
# speedup vs baseline: 1.0083x; 1.0038x over previous
.LBB0_201:
	s_lshl_b32 s100, s4, 8
	s_or_b32 s100, s100, s56
	v_lshl_add_u32 v230, v147, 3, s100
	v_ashrrev_i32_e32 v231, 31, v230
	v_lshl_add_u64 v[230:231], v[230:231], 2, s[10:11]
	global_load_dwordx4 v[232:235], v[230:231], off
	global_load_dwordx4 v[236:239], v[230:231], off offset:16
	global_load_dwordx4 v[240:243], v[230:231], off offset:528
	global_load_dwordx4 v[244:247], v[230:231], off offset:512
	s_ashr_i32 s21, s20, 31
	s_lshl_b64 s[22:23], s[20:21], 20
	s_add_u32 s22, s36, s22
	s_addc_u32 s23, s37, s23
	s_and_b64 s[24:25], s[0:1], exec
	s_cselect_b32 s5, s23, s29
	s_cselect_b32 s21, s22, s28
	s_ashr_i32 s19, s18, 31
	s_lshl_b64 s[24:25], s[18:19], 20
	s_add_u32 s24, s62, s24
	s_addc_u32 s25, s63, s25
	s_and_b64 s[34:35], s[0:1], exec
	s_cselect_b32 s19, s25, s31
	s_cselect_b32 s72, s24, s30
	s_add_u32 s28, s28, 0x80080
	s_addc_u32 s29, s29, 0
	s_add_u32 s73, s30, 0x100
	v_mov_b32_e32 v0, 0
	s_addc_u32 s74, s31, 0
	s_mov_b32 s75, -2
	v_mov_b32_e32 v1, 0
	v_pk_mov_b32 v[2:3], v[0:1], v[0:1]
	v_pk_mov_b32 v[4:5], v[0:1], v[0:1]
	v_pk_mov_b32 v[6:7], v[0:1], v[0:1]
	v_pk_mov_b32 v[8:9], v[0:1], v[0:1]
	v_pk_mov_b32 v[10:11], v[0:1], v[0:1]
	v_pk_mov_b32 v[12:13], v[0:1], v[0:1]
	v_pk_mov_b32 v[14:15], v[0:1], v[0:1]
	v_pk_mov_b32 v[16:17], v[0:1], v[0:1]
	v_pk_mov_b32 v[18:19], v[0:1], v[0:1]
	v_pk_mov_b32 v[20:21], v[0:1], v[0:1]
	v_pk_mov_b32 v[22:23], v[0:1], v[0:1]
	v_pk_mov_b32 v[24:25], v[0:1], v[0:1]
	v_pk_mov_b32 v[26:27], v[0:1], v[0:1]
	v_pk_mov_b32 v[28:29], v[0:1], v[0:1]
	v_pk_mov_b32 v[30:31], v[0:1], v[0:1]
	v_pk_mov_b32 v[32:33], v[0:1], v[0:1]
	v_pk_mov_b32 v[34:35], v[0:1], v[0:1]
	v_pk_mov_b32 v[36:37], v[0:1], v[0:1]
	v_pk_mov_b32 v[38:39], v[0:1], v[0:1]
	v_pk_mov_b32 v[40:41], v[0:1], v[0:1]
	v_pk_mov_b32 v[42:43], v[0:1], v[0:1]
	v_pk_mov_b32 v[44:45], v[0:1], v[0:1]
	v_pk_mov_b32 v[46:47], v[0:1], v[0:1]
	v_pk_mov_b32 v[48:49], v[0:1], v[0:1]
	v_pk_mov_b32 v[50:51], v[0:1], v[0:1]
	v_pk_mov_b32 v[56:57], v[0:1], v[0:1]
	v_pk_mov_b32 v[58:59], v[0:1], v[0:1]
	v_pk_mov_b32 v[68:69], v[0:1], v[0:1]
	v_pk_mov_b32 v[70:71], v[0:1], v[0:1]
	v_pk_mov_b32 v[76:77], v[0:1], v[0:1]
	v_pk_mov_b32 v[78:79], v[0:1], v[0:1]
	v_pk_mov_b32 v[80:81], v[0:1], v[0:1]
	v_pk_mov_b32 v[82:83], v[0:1], v[0:1]
	v_pk_mov_b32 v[84:85], v[0:1], v[0:1]
	v_pk_mov_b32 v[86:87], v[0:1], v[0:1]
	v_pk_mov_b32 v[88:89], v[0:1], v[0:1]
	v_pk_mov_b32 v[90:91], v[0:1], v[0:1]
	v_pk_mov_b32 v[92:93], v[0:1], v[0:1]
	v_pk_mov_b32 v[94:95], v[0:1], v[0:1]
	v_pk_mov_b32 v[96:97], v[0:1], v[0:1]
	v_pk_mov_b32 v[98:99], v[0:1], v[0:1]
	v_pk_mov_b32 v[100:101], v[0:1], v[0:1]
	v_pk_mov_b32 v[102:103], v[0:1], v[0:1]
	v_pk_mov_b32 v[104:105], v[0:1], v[0:1]
	v_pk_mov_b32 v[106:107], v[0:1], v[0:1]
	v_pk_mov_b32 v[108:109], v[0:1], v[0:1]
	v_pk_mov_b32 v[110:111], v[0:1], v[0:1]
	v_pk_mov_b32 v[112:113], v[0:1], v[0:1]
	v_pk_mov_b32 v[114:115], v[0:1], v[0:1]
	v_pk_mov_b32 v[116:117], v[0:1], v[0:1]
	v_pk_mov_b32 v[118:119], v[0:1], v[0:1]
	v_pk_mov_b32 v[120:121], v[0:1], v[0:1]
	v_pk_mov_b32 v[122:123], v[0:1], v[0:1]
	v_pk_mov_b32 v[124:125], v[0:1], v[0:1]
	v_pk_mov_b32 v[126:127], v[0:1], v[0:1]
	v_pk_mov_b32 v[128:129], v[0:1], v[0:1]
	v_pk_mov_b32 v[130:131], v[0:1], v[0:1]
	v_pk_mov_b32 v[132:133], v[0:1], v[0:1]
	v_pk_mov_b32 v[134:135], v[0:1], v[0:1]
	v_pk_mov_b32 v[136:137], v[0:1], v[0:1]
	v_pk_mov_b32 v[138:139], v[0:1], v[0:1]
	v_pk_mov_b32 v[140:141], v[0:1], v[0:1]
	v_pk_mov_b32 v[142:143], v[0:1], v[0:1]

.LBB0_320:
	v_cndmask_b32_e64 v74, v188, v49, s[10:11]
	v_cndmask_b32_e64 v64, v48, v188, s[8:9]
	v_cndmask_b32_e64 v75, v64, v48, s[10:11]
	v_cndmask_b32_e64 v76, v50, v188, s[12:13]
	v_cndmask_b32_e64 v77, v51, v188, s[14:15]
	v_cndmask_b32_e64 v78, v52, v188, s[16:17]
	v_cndmask_b32_e64 v66, v53, v188, s[18:19]
	v_cndmask_b32_e64 v65, v54, v188, s[20:21]
	v_cndmask_b32_e64 v64, v55, v188, s[22:23]
	v_cndmask_b32_e64 v56, v56, v188, s[24:25]
	v_cndmask_b32_e64 v55, v57, v188, s[26:27]
	v_cndmask_b32_e64 v54, v58, v188, s[28:29]
	v_cndmask_b32_e64 v53, v59, v188, s[30:31]
	v_cndmask_b32_e64 v52, v60, v188, s[34:35]
	v_cndmask_b32_e64 v51, v61, v188, s[36:37]
	v_cndmask_b32_e64 v50, v62, v188, s[38:39]
	v_cndmask_b32_e64 v48, v63, v188, s[40:41]
	v_add_u32_e32 v228, s69, v175
	v_exp_f32_e32 v57, v120
	v_exp_f32_e32 v58, v189
	v_exp_f32_e32 v59, v161
	v_exp_f32_e32 v61, v159
	v_add_f32_e32 v60, 0, v57
	v_exp_f32_e32 v62, v157
	v_add_f32_e32 v60, v58, v60
	v_exp_f32_e32 v63, v126
	v_add_f32_e32 v60, v59, v60
	v_exp_f32_e32 v79, v123
	v_add_f32_e32 v60, v61, v60
	v_exp_f32_e32 v120, v122
	v_add_f32_e32 v60, v62, v60
	v_exp_f32_e32 v121, v121
	v_add_f32_e32 v60, v63, v60
	v_exp_f32_e32 v73, v73
	v_add_f32_e32 v60, v79, v60
	v_exp_f32_e32 v72, v72
	v_add_f32_e32 v60, v120, v60
	v_exp_f32_e32 v71, v71
	v_add_f32_e32 v60, v121, v60
	v_exp_f32_e32 v70, v70
	v_add_f32_e32 v60, v73, v60
	v_exp_f32_e32 v69, v69
	v_add_f32_e32 v60, v72, v60
	v_exp_f32_e32 v68, v68
	v_add_f32_e32 v60, v71, v60
	v_exp_f32_e32 v67, v67
	v_add_f32_e32 v60, v70, v60
	v_exp_f32_e32 v122, v32
	v_add_f32_e32 v60, v69, v60
	v_exp_f32_e32 v123, v33
	v_add_f32_e32 v60, v68, v60
	v_exp_f32_e32 v126, v34
	v_add_f32_e32 v32, v67, v60
	v_exp_f32_e32 v60, v35
	v_add_f32_e32 v32, v122, v32
	v_exp_f32_e32 v157, v36
	v_add_f32_e32 v32, v123, v32
	v_exp_f32_e32 v159, v37
	v_add_f32_e32 v32, v126, v32
	v_exp_f32_e32 v161, v38
	v_add_f32_e32 v32, v60, v32
	v_exp_f32_e32 v189, v39
	v_add_f32_e32 v32, v157, v32
	v_exp_f32_e32 v190, v40
	v_add_f32_e32 v32, v159, v32
	v_exp_f32_e32 v191, v41
	v_add_f32_e32 v32, v161, v32
	v_exp_f32_e32 v192, v42
	v_add_f32_e32 v32, v189, v32
	v_exp_f32_e32 v198, v43
	v_add_f32_e32 v32, v190, v32
	v_exp_f32_e32 v199, v44
	v_add_f32_e32 v32, v191, v32
	v_exp_f32_e32 v200, v45
	v_add_f32_e32 v32, v192, v32
	v_exp_f32_e32 v201, v46
	v_add_f32_e32 v32, v198, v32
	v_exp_f32_e32 v202, v47
	v_add_f32_e32 v32, v199, v32
	v_exp_f32_e32 v203, v16
	v_add_f32_e32 v32, v200, v32
	v_exp_f32_e32 v204, v17
	v_add_f32_e32 v32, v201, v32
	v_exp_f32_e32 v205, v18
	v_add_f32_e32 v16, v202, v32
	v_exp_f32_e32 v206, v19
	v_add_f32_e32 v16, v203, v16
	v_exp_f32_e32 v207, v20
	v_add_f32_e32 v16, v204, v16
	v_exp_f32_e32 v208, v21
	v_add_f32_e32 v16, v205, v16
	v_exp_f32_e32 v209, v22
	v_add_f32_e32 v16, v206, v16
	v_exp_f32_e32 v210, v23
	v_add_f32_e32 v16, v207, v16
	v_exp_f32_e32 v211, v24
	v_add_f32_e32 v16, v208, v16
	v_exp_f32_e32 v212, v25
	v_add_f32_e32 v16, v209, v16
	v_exp_f32_e32 v213, v26
	v_add_f32_e32 v16, v210, v16
	v_exp_f32_e32 v214, v27
	v_add_f32_e32 v16, v211, v16
	v_exp_f32_e32 v215, v28
	v_add_f32_e32 v16, v212, v16
	v_exp_f32_e32 v216, v29
	v_add_f32_e32 v16, v213, v16
	v_exp_f32_e32 v217, v30
	v_add_f32_e32 v16, v214, v16
	v_exp_f32_e32 v218, v31
	v_add_f32_e32 v16, v215, v16
	v_exp_f32_e32 v219, v0
	v_add_f32_e32 v16, v216, v16
	v_exp_f32_e32 v220, v1
	v_add_f32_e32 v16, v217, v16
	v_exp_f32_e32 v221, v2
	v_add_f32_e32 v0, v218, v16
	v_exp_f32_e32 v222, v3
	v_add_f32_e32 v0, v219, v0
	v_exp_f32_e32 v223, v4
	v_add_f32_e32 v0, v220, v0
	v_exp_f32_e32 v224, v5
	v_add_f32_e32 v0, v221, v0
	v_exp_f32_e32 v225, v6
	v_add_f32_e32 v0, v222, v0
	v_add_f32_e32 v0, v223, v0
	v_add_f32_e32 v0, v224, v0
	v_add_f32_e32 v4, v225, v0
	v_exp_f32_e32 v226, v7
	v_exp_f32_e32 v227, v8
	ds_read2_b64 v[0:3], v228 offset1:2
	v_add_f32_e32 v4, v226, v4
	v_cvt_pk_bf16_f32 v5, v59, v61
	v_add_f32_e32 v229, v227, v4
	v_cvt_pk_bf16_f32 v4, v57, v58
	v_cvt_pk_bf16_f32 v6, v62, v63
	v_cvt_pk_bf16_f32 v7, v79, v120
	v_add_u32_e32 v57, s69, v174
	ds_read2_b64 v[16:19], v57 offset1:2
	s_waitcnt lgkmcnt(1)
	v_mfma_f32_32x32x16_bf16 v[32:47], v[0:3], v[4:7], 0
	v_exp_f32_e32 v58, v9
	v_exp_f32_e32 v59, v10
	v_exp_f32_e32 v61, v11
	ds_read2_b64 v[0:3], v228 offset0:4 offset1:6
	s_waitcnt lgkmcnt(1)
	v_mfma_f32_32x32x16_bf16 v[16:31], v[16:19], v[4:7], 0
	v_exp_f32_e32 v12, v12
	v_cvt_pk_bf16_f32 v8, v121, v73
	v_cvt_pk_bf16_f32 v9, v72, v71
	v_cvt_pk_bf16_f32 v10, v70, v69
	v_cvt_pk_bf16_f32 v11, v68, v67
	ds_read2_b64 v[4:7], v57 offset0:4 offset1:6
	s_waitcnt lgkmcnt(1)
	v_mfma_f32_32x32x16_bf16 v[32:47], v[0:3], v[8:11], v[32:47]
	v_add_f32_e32 v0, v58, v229
	v_add_f32_e32 v0, v59, v0
	v_add_f32_e32 v0, v61, v0
	v_add_f32_e32 v62, v12, v0
	v_exp_f32_e32 v13, v13
	ds_read2_b64 v[0:3], v228 offset0:8 offset1:10
	s_waitcnt lgkmcnt(1)
	v_mfma_f32_32x32x16_bf16 v[16:31], v[4:7], v[8:11], v[16:31]
	v_exp_f32_e32 v14, v14
	v_cvt_pk_bf16_f32 v4, v122, v123
	v_cvt_pk_bf16_f32 v5, v126, v60
	v_cvt_pk_bf16_f32 v6, v157, v159
	v_cvt_pk_bf16_f32 v7, v161, v189
	ds_read2_b64 v[8:11], v57 offset0:8 offset1:10
	v_exp_f32_e32 v48, v48
	s_waitcnt lgkmcnt(1)
	v_mfma_f32_32x32x16_bf16 v[32:47], v[0:3], v[4:7], v[32:47]
	v_add_f32_e32 v0, v13, v62
	v_add_f32_e32 v60, v14, v0
	v_exp_f32_e32 v15, v15
	v_exp_f32_e32 v62, v75
	ds_read2_b64 v[0:3], v228 offset0:12 offset1:14
	s_waitcnt lgkmcnt(1)
	v_mfma_f32_32x32x16_bf16 v[16:31], v[8:11], v[4:7], v[16:31]
	v_add_f32_e32 v4, v15, v60
	v_add_f32_e32 v60, v62, v4
	v_cvt_pk_bf16_f32 v4, v190, v191
	v_cvt_pk_bf16_f32 v5, v192, v198
	v_cvt_pk_bf16_f32 v6, v199, v200
	v_cvt_pk_bf16_f32 v7, v201, v202
	ds_read2_b64 v[8:11], v57 offset0:12 offset1:14
	s_waitcnt lgkmcnt(1)
	v_mfma_f32_32x32x16_bf16 v[32:47], v[0:3], v[4:7], v[32:47]
	v_exp_f32_e32 v63, v74
	v_exp_f32_e32 v67, v76
	v_exp_f32_e32 v68, v77
	ds_read2_b64 v[0:3], v228 offset0:16 offset1:18
	s_waitcnt lgkmcnt(1)
	v_mfma_f32_32x32x16_bf16 v[16:31], v[8:11], v[4:7], v[16:31]
	v_exp_f32_e32 v69, v78
	v_cvt_pk_bf16_f32 v4, v203, v204
	v_cvt_pk_bf16_f32 v5, v205, v206
	v_cvt_pk_bf16_f32 v6, v207, v208
	v_cvt_pk_bf16_f32 v7, v209, v210
	ds_read2_b64 v[8:11], v57 offset0:16 offset1:18
	s_waitcnt lgkmcnt(1)
	v_mfma_f32_32x32x16_bf16 v[32:47], v[0:3], v[4:7], v[32:47]
	v_add_f32_e32 v0, v63, v60
	v_add_f32_e32 v0, v67, v0
	v_add_f32_e32 v0, v68, v0
	v_add_f32_e32 v60, v69, v0
	v_exp_f32_e32 v66, v66
	ds_read2_b64 v[0:3], v228 offset0:20 offset1:22
	s_waitcnt lgkmcnt(1)
	v_mfma_f32_32x32x16_bf16 v[16:31], v[8:11], v[4:7], v[16:31]
	v_exp_f32_e32 v65, v65
	v_cvt_pk_bf16_f32 v4, v211, v212
	v_cvt_pk_bf16_f32 v5, v213, v214
	v_cvt_pk_bf16_f32 v6, v215, v216
	v_cvt_pk_bf16_f32 v7, v217, v218
	ds_read2_b64 v[8:11], v57 offset0:20 offset1:22
	s_waitcnt lgkmcnt(1)
	v_mfma_f32_32x32x16_bf16 v[32:47], v[0:3], v[4:7], v[32:47]
	v_add_f32_e32 v0, v66, v60
	v_add_f32_e32 v60, v65, v0
	v_exp_f32_e32 v64, v64
	v_exp_f32_e32 v56, v56
	ds_read2_b64 v[0:3], v228 offset0:24 offset1:26
	s_waitcnt lgkmcnt(1)
	v_mfma_f32_32x32x16_bf16 v[16:31], v[8:11], v[4:7], v[16:31]
	v_exp_f32_e32 v55, v55
	v_cvt_pk_bf16_f32 v4, v219, v220
	v_cvt_pk_bf16_f32 v5, v221, v222
	v_cvt_pk_bf16_f32 v6, v223, v224
	v_cvt_pk_bf16_f32 v7, v225, v226
	ds_read2_b64 v[8:11], v57 offset0:24 offset1:26
	s_waitcnt lgkmcnt(1)
	v_mfma_f32_32x32x16_bf16 v[32:47], v[0:3], v[4:7], v[32:47]
	v_exp_f32_e32 v54, v54
	v_add_f32_e32 v0, v64, v60
	v_add_f32_e32 v0, v56, v0
	v_add_f32_e32 v0, v55, v0
	v_add_f32_e32 v60, v54, v0
	ds_read2_b64 v[0:3], v228 offset0:28 offset1:30
	s_waitcnt lgkmcnt(1)
	v_mfma_f32_32x32x16_bf16 v[16:31], v[8:11], v[4:7], v[16:31]
	v_exp_f32_e32 v53, v53
	v_cvt_pk_bf16_f32 v4, v227, v58
	v_cvt_pk_bf16_f32 v5, v59, v61
	v_cvt_pk_bf16_f32 v6, v12, v13
	v_cvt_pk_bf16_f32 v7, v14, v15
	ds_read2_b64 v[8:11], v57 offset0:28 offset1:30
	s_waitcnt lgkmcnt(1)
	v_mfma_f32_32x32x16_bf16 v[32:47], v[0:3], v[4:7], v[32:47]
	v_exp_f32_e32 v13, v52
	v_exp_f32_e32 v14, v51
	ds_read2_b64 v[0:3], v228 offset0:32 offset1:34
	v_exp_f32_e32 v15, v50
	v_add_f32_e32 v12, v53, v60
	s_waitcnt lgkmcnt(1)
	v_mfma_f32_32x32x16_bf16 v[16:31], v[8:11], v[4:7], v[16:31]
	v_cvt_pk_bf16_f32 v4, v62, v63
	v_cvt_pk_bf16_f32 v5, v67, v68
	v_cvt_pk_bf16_f32 v6, v69, v66
	v_cvt_pk_bf16_f32 v7, v65, v64
	ds_read2_b64 v[8:11], v57 offset0:32 offset1:34
	s_waitcnt lgkmcnt(1)
	v_mfma_f32_32x32x16_bf16 v[32:47], v[0:3], v[4:7], v[32:47]
	v_add_f32_e32 v0, v13, v12
	v_add_f32_e32 v0, v14, v0
	v_add_f32_e32 v0, v15, v0
	v_add_f32_e32 v12, v48, v0
	ds_read2_b64 v[0:3], v228 offset0:36 offset1:38
	ds_bpermute_b32 v50, v171, v12
	s_waitcnt lgkmcnt(2)
	v_mfma_f32_32x32x16_bf16 v[16:31], v[8:11], v[4:7], v[16:31]
	v_exp_f32_e32 v49, v155
	v_cvt_pk_bf16_f32 v4, v56, v55
	v_cvt_pk_bf16_f32 v5, v54, v53
	v_cvt_pk_bf16_f32 v6, v13, v14
	v_cvt_pk_bf16_f32 v7, v15, v48
	ds_read2_b64 v[8:11], v57 offset0:36 offset1:38
	s_waitcnt lgkmcnt(2)
	v_mfma_f32_32x32x16_bf16 v[32:47], v[0:3], v[4:7], v[32:47]
	s_waitcnt lgkmcnt(1)
	v_add_f32_e32 v0, v12, v50
	v_add_f32_e32 v0, v49, v0
	v_div_scale_f32 v1, s[74:75], v0, v0, 1.0
	v_rcp_f32_e32 v2, v1
	s_nop 0
	v_fma_f32 v3, -v1, v2, 1.0
	v_fmac_f32_e32 v2, v3, v2
	v_div_scale_f32 v3, vcc, 1.0, v0, 1.0
	s_waitcnt lgkmcnt(0)
	v_mfma_f32_32x32x16_bf16 v[16:31], v[8:11], v[4:7], v[16:31]
	v_mul_f32_e32 v4, v3, v2
	v_fma_f32 v5, -v1, v4, v3
	v_fmac_f32_e32 v4, v5, v2
	v_fma_f32 v1, -v1, v4, v3
	v_div_fmas_f32 v1, v1, v2, v4
	v_div_fixup_f32 v48, v1, v0, 1.0
	v_pk_mul_f32 v[0:1], v[32:33], v[48:49] op_sel_hi:[1,0]
	v_pk_mul_f32 v[2:3], v[34:35], v[48:49] op_sel_hi:[1,0]
	v_pk_mul_f32 v[50:51], v[0:1], v[0:1]
	v_pk_mul_f32 v[34:35], v[2:3], v[2:3]
	v_pk_mul_f32 v[4:5], v[36:37], v[48:49] op_sel_hi:[1,0]
	v_pk_mul_f32 v[6:7], v[38:39], v[48:49] op_sel_hi:[1,0]
	v_pk_mul_f32 v[8:9], v[40:41], v[48:49] op_sel_hi:[1,0]
	v_pk_mul_f32 v[10:11], v[42:43], v[48:49] op_sel_hi:[1,0]
	v_pk_mul_f32 v[12:13], v[44:45], v[48:49] op_sel_hi:[1,0]
	v_pk_mul_f32 v[32:33], v[46:47], v[48:49] op_sel_hi:[1,0]
	v_pk_mul_f32 v[14:15], v[16:17], v[48:49] op_sel_hi:[1,0]
	v_pk_mul_f32 v[16:17], v[18:19], v[48:49] op_sel_hi:[1,0]
	v_pk_mul_f32 v[18:19], v[20:21], v[48:49] op_sel_hi:[1,0]
	v_pk_mul_f32 v[20:21], v[22:23], v[48:49] op_sel_hi:[1,0]
	v_pk_mul_f32 v[22:23], v[24:25], v[48:49] op_sel_hi:[1,0]
	v_pk_mul_f32 v[24:25], v[26:27], v[48:49] op_sel_hi:[1,0]
	v_pk_mul_f32 v[26:27], v[28:29], v[48:49] op_sel_hi:[1,0]
	v_pk_mul_f32 v[28:29], v[30:31], v[48:49] op_sel_hi:[1,0]
	v_add_f32_e32 v48, v50, v51
	v_add_f32_e32 v34, v34, v48
	v_pk_mul_f32 v[36:37], v[4:5], v[4:5]
	v_add_f32_e32 v34, v35, v34
	v_add_f32_e32 v34, v36, v34
	v_pk_mul_f32 v[38:39], v[6:7], v[6:7]
	v_add_f32_e32 v34, v37, v34
	v_add_f32_e32 v34, v38, v34
	v_pk_mul_f32 v[40:41], v[8:9], v[8:9]
	v_add_f32_e32 v34, v39, v34
	v_add_f32_e32 v34, v40, v34
	v_pk_mul_f32 v[42:43], v[10:11], v[10:11]
	v_add_f32_e32 v34, v41, v34
	v_add_f32_e32 v34, v42, v34
	v_pk_mul_f32 v[44:45], v[12:13], v[12:13]
	v_add_f32_e32 v34, v43, v34
	v_add_f32_e32 v34, v44, v34
	v_pk_mul_f32 v[46:47], v[32:33], v[32:33]
	v_add_f32_e32 v34, v45, v34
	v_add_f32_e32 v34, v46, v34
	v_pk_mul_f32 v[52:53], v[14:15], v[14:15]
	v_add_f32_e32 v34, v47, v34
	v_add_f32_e32 v34, v52, v34
	v_pk_mul_f32 v[54:55], v[16:17], v[16:17]
	v_add_f32_e32 v34, v53, v34
	v_add_f32_e32 v34, v54, v34
	v_pk_mul_f32 v[56:57], v[18:19], v[18:19]
	v_add_f32_e32 v34, v55, v34
	v_add_f32_e32 v34, v56, v34
	v_pk_mul_f32 v[58:59], v[20:21], v[20:21]
	v_add_f32_e32 v34, v57, v34
	v_add_f32_e32 v34, v58, v34
	v_pk_mul_f32 v[60:61], v[22:23], v[22:23]
	v_add_f32_e32 v34, v59, v34
	v_add_f32_e32 v34, v60, v34
	v_pk_mul_f32 v[62:63], v[24:25], v[24:25]
	v_add_f32_e32 v34, v61, v34
	v_add_f32_e32 v34, v62, v34
	v_pk_mul_f32 v[64:65], v[26:27], v[26:27]
	v_add_f32_e32 v34, v63, v34
	v_add_f32_e32 v34, v64, v34
	v_pk_mul_f32 v[30:31], v[28:29], v[28:29]
	v_add_f32_e32 v34, v65, v34
	v_add_f32_e32 v30, v30, v34
	v_add_f32_e32 v30, v31, v30
	ds_bpermute_b32 v31, v171, v30
	s_and_saveexec_b64 s[74:75], s[6:7]
	s_cbranch_execz .LBB0_314
	s_waitcnt lgkmcnt(0)
	v_add_f32_e32 v30, v30, v31
	ds_write_b32 v151, v30
	s_branch .LBB0_314

.LBB0_528:
	s_mov_b32 s66, s38
	s_add_i32 s38, s38, 1
	s_cmp_lt_u32 s66, 3
	s_mov_b64 s[2:3], s[6:7]
	s_cselect_b64 s[24:25], -1, 0
	s_lshl_b32 s6, s38, 5
	s_mov_b32 s26, s57
	s_mov_b32 s67, s57
	s_add_i32 s57, s6, s0
	s_and_b64 s[6:7], s[24:25], exec
	s_cselect_b32 s6, s57, s26
	s_ashr_i32 s7, s6, 31
	s_lshl_b64 s[6:7], s[6:7], 20
	s_add_u32 s6, s30, s6
	s_addc_u32 s7, s31, s7
	s_and_b64 s[24:25], s[24:25], exec
	s_cselect_b32 s68, s7, s3
	s_cselect_b32 s69, s6, s2
	s_add_u32 s2, s2, 0x80080
	v_mov_b32_e32 v0, 0
	s_addc_u32 s3, s3, 0
	s_mov_b32 s70, -2
	s_mov_b64 s[24:25], s[22:23]
	v_mov_b32_e32 v1, 0
	v_pk_mov_b32 v[2:3], v[0:1], v[0:1]
	v_pk_mov_b32 v[4:5], v[0:1], v[0:1]
	v_pk_mov_b32 v[6:7], v[0:1], v[0:1]
	v_pk_mov_b32 v[8:9], v[0:1], v[0:1]
	v_pk_mov_b32 v[10:11], v[0:1], v[0:1]
	v_pk_mov_b32 v[12:13], v[0:1], v[0:1]
	v_pk_mov_b32 v[14:15], v[0:1], v[0:1]
	v_pk_mov_b32 v[16:17], v[0:1], v[0:1]
	v_pk_mov_b32 v[18:19], v[0:1], v[0:1]
	v_pk_mov_b32 v[20:21], v[0:1], v[0:1]
	v_pk_mov_b32 v[22:23], v[0:1], v[0:1]
	v_pk_mov_b32 v[24:25], v[0:1], v[0:1]
	v_pk_mov_b32 v[26:27], v[0:1], v[0:1]
	v_pk_mov_b32 v[28:29], v[0:1], v[0:1]
	v_pk_mov_b32 v[30:31], v[0:1], v[0:1]
	v_pk_mov_b32 v[32:33], v[0:1], v[0:1]
	v_pk_mov_b32 v[34:35], v[0:1], v[0:1]
	v_pk_mov_b32 v[36:37], v[0:1], v[0:1]
	v_pk_mov_b32 v[38:39], v[0:1], v[0:1]
	v_pk_mov_b32 v[40:41], v[0:1], v[0:1]
	v_pk_mov_b32 v[42:43], v[0:1], v[0:1]
	v_pk_mov_b32 v[44:45], v[0:1], v[0:1]
	v_pk_mov_b32 v[46:47], v[0:1], v[0:1]
	v_pk_mov_b32 v[48:49], v[0:1], v[0:1]
	v_pk_mov_b32 v[50:51], v[0:1], v[0:1]
	v_pk_mov_b32 v[52:53], v[0:1], v[0:1]
	v_pk_mov_b32 v[54:55], v[0:1], v[0:1]
	v_pk_mov_b32 v[56:57], v[0:1], v[0:1]
	v_pk_mov_b32 v[58:59], v[0:1], v[0:1]
	v_pk_mov_b32 v[60:61], v[0:1], v[0:1]
	v_pk_mov_b32 v[62:63], v[0:1], v[0:1]
	v_pk_mov_b32 v[64:65], v[0:1], v[0:1]
	v_pk_mov_b32 v[66:67], v[0:1], v[0:1]
	v_pk_mov_b32 v[68:69], v[0:1], v[0:1]
	v_pk_mov_b32 v[70:71], v[0:1], v[0:1]
	v_pk_mov_b32 v[72:73], v[0:1], v[0:1]
	v_pk_mov_b32 v[74:75], v[0:1], v[0:1]
	v_pk_mov_b32 v[76:77], v[0:1], v[0:1]
	v_pk_mov_b32 v[78:79], v[0:1], v[0:1]
	v_pk_mov_b32 v[80:81], v[0:1], v[0:1]
	v_pk_mov_b32 v[82:83], v[0:1], v[0:1]
	v_pk_mov_b32 v[84:85], v[0:1], v[0:1]
	v_pk_mov_b32 v[86:87], v[0:1], v[0:1]
	v_pk_mov_b32 v[88:89], v[0:1], v[0:1]
	v_pk_mov_b32 v[90:91], v[0:1], v[0:1]
	v_pk_mov_b32 v[92:93], v[0:1], v[0:1]
	v_pk_mov_b32 v[94:95], v[0:1], v[0:1]
	v_pk_mov_b32 v[112:113], v[0:1], v[0:1]
	v_pk_mov_b32 v[114:115], v[0:1], v[0:1]
	v_pk_mov_b32 v[116:117], v[0:1], v[0:1]
	v_pk_mov_b32 v[118:119], v[0:1], v[0:1]
	v_pk_mov_b32 v[120:121], v[0:1], v[0:1]
	v_pk_mov_b32 v[122:123], v[0:1], v[0:1]
	v_pk_mov_b32 v[124:125], v[0:1], v[0:1]
	v_pk_mov_b32 v[126:127], v[0:1], v[0:1]
	v_pk_mov_b32 v[128:129], v[0:1], v[0:1]
	v_pk_mov_b32 v[130:131], v[0:1], v[0:1]
	v_pk_mov_b32 v[132:133], v[0:1], v[0:1]
	v_pk_mov_b32 v[134:135], v[0:1], v[0:1]
	v_pk_mov_b32 v[136:137], v[0:1], v[0:1]
	v_pk_mov_b32 v[138:139], v[0:1], v[0:1]
	v_pk_mov_b32 v[140:141], v[0:1], v[0:1]
	v_pk_mov_b32 v[142:143], v[0:1], v[0:1]
